# GLU GEMM units appended to the per-XCD work list (items 88..95, gated on the S5 counters as before); stage-2 list empty, one fewer stage transition
# baseline (speedup 1.0000x reference)
.LBB0_416:
	s_cmp_lg_u32 s10, 0
	s_cselect_b64 s[90:91], -1, 0
	s_cmp_lg_u32 s10, 1
	s_cselect_b64 s[60:61], -1, 0
	s_cmp_eq_u32 s10, 1
	v_readlane_b32 s4, v254, 44
	v_readlane_b32 s5, v254, 48
	s_cselect_b32 s51, 0, 0
	s_cselect_b32 s4, s5, s4
	s_cmp_eq_u32 s10, 0
	v_readlane_b32 s5, v254, 47
	s_cselect_b32 s70, s5, s4
	s_cselect_b32 s51, 0x60, s51
	s_cmp_lg_u32 s10, 2
	v_writelane_b32 v255, s10, 6
	s_cselect_b64 s[52:53], -1, 0
	s_mov_b32 s71, s59
	s_mov_b32 s7, 0
	s_branch .LBB0_419

.Lmx_glu_go:
	s_mov_b64 s[10:11], s[0:1]
	s_load_dwordx2 s[24:25], s[10:11], 0x100
	s_mov_b64 s[10:11], s[0:1]
	s_load_dwordx2 s[22:23], s[10:11], 0x100
	s_mov_b64 s[18:19], s[0:1]
	s_mov_b64 s[10:11], s[0:1]
	s_load_dwordx2 s[12:13], s[10:11], 0x100
	s_mov_b64 s[10:11], s[0:1]
	s_mov_b64 s[14:15], s[0:1]
	s_load_dwordx2 s[10:11], s[10:11], 0x100
	s_load_dwordx2 s[16:17], s[14:15], 0x88
	v_mov_b32_e32 v8, v214
	s_nop 0
	v_readfirstlane_b32 s4, v8
	s_and_saveexec_b64 s[14:15], s[46:47]
	s_cbranch_execz .LBB0_447
	s_load_dwordx2 s[18:19], s[18:19], 0x100
	s_lshl_b32 s20, s76, 2
	s_andn2_b32 s20, s20, 63
	s_add_i32 s20, s20, s79
	s_ashr_i32 s21, s20, 31
	s_lshl_b64 s[20:21], s[20:21], 2
	s_waitcnt lgkmcnt(0)
	s_add_u32 s18, s18, s20
	s_addc_u32 s19, s19, s21
	s_add_u32 s18, s18, 0x6000
	s_addc_u32 s19, s19, 0
	s_mov_b32 s26, 0x400001
	s_branch .LBB0_440

.LBB0_473:
	s_cmp_lt_i32 s76, 88
	s_cbranch_scc1 .Lmx_dec
	s_sub_i32 s76, s76, 88
	s_lshl_b32 s76, s76, 3
	s_add_i32 s76, s76, s5
	s_branch .Lmx_glu_go
